# grid barrier leader: its own L1 invalidate issued together with the L2 writeback (before the top-level arrive) instead of after the release
# speedup vs baseline: 1.0027x; 1.0027x over previous
.LBB0_51:
	s_andn2_saveexec_b64 s[6:7], s[6:7]
	s_cbranch_execz .LBB0_71
	s_mov_b64 s[6:7], exec
	buffer_inv sc1
	buffer_wbl2 sc1
	s_waitcnt lgkmcnt(0)
	s_waitcnt vmcnt(0)
	v_mbcnt_lo_u32_b32 v2, s6, 0
	v_mbcnt_hi_u32_b32 v2, s7, v2
	v_cmp_eq_u32_e32 vcc, 0, v2
	s_and_saveexec_b64 s[10:11], vcc
	s_cbranch_execz .LBB0_54
	s_bcnt1_i32_b64 s6, s[6:7]
	v_mov_b32_e32 v3, 0x3000
	v_mov_b32_e32 v4, s6
	global_atomic_add v3, v3, v4, s[14:15] offset:1024 sc0

.LBB0_68:
	s_or_b64 exec, exec, s[6:7]
	s_mov_b64 s[6:7], exec
	v_mbcnt_lo_u32_b32 v1, s6, 0
	v_mbcnt_hi_u32_b32 v1, s7, v1
	v_cmp_eq_u32_e32 vcc, 0, v1
	s_and_saveexec_b64 s[10:11], vcc
	s_cbranch_execz .LBB0_70
	s_bcnt1_i32_b64 s6, s[6:7]
	v_mov_b32_e32 v1, 0x2000
	v_mov_b32_e32 v2, s6
	global_atomic_add v1, v2, s[4:5] offset:1024
.LBB0_70:
	s_or_b64 exec, exec, s[10:11]
	s_waitcnt vmcnt(0)

.LBB0_252:
	s_andn2_saveexec_b64 s[6:7], s[6:7]
	s_cbranch_execz .LBB0_272
	s_mov_b64 s[6:7], exec
	buffer_inv sc1
	buffer_wbl2 sc1
	s_waitcnt lgkmcnt(0)
	s_waitcnt vmcnt(0)
	v_mbcnt_lo_u32_b32 v2, s6, 0
	v_mbcnt_hi_u32_b32 v2, s7, v2
	v_cmp_eq_u32_e32 vcc, 0, v2
	s_and_saveexec_b64 s[8:9], vcc
	s_cbranch_execz .LBB0_255
	s_bcnt1_i32_b64 s6, s[6:7]
	v_mov_b32_e32 v3, 0x3000
	v_mov_b32_e32 v4, s6
	global_atomic_add v3, v3, v4, s[14:15] offset:1024 sc0

.LBB0_269:
	s_or_b64 exec, exec, s[6:7]
	s_mov_b64 s[6:7], exec
	v_mbcnt_lo_u32_b32 v1, s6, 0
	v_mbcnt_hi_u32_b32 v1, s7, v1
	v_cmp_eq_u32_e32 vcc, 0, v1
	s_and_saveexec_b64 s[8:9], vcc
	s_cbranch_execz .LBB0_271
	s_bcnt1_i32_b64 s6, s[6:7]
	v_mov_b32_e32 v1, 0x2000
	v_mov_b32_e32 v2, s6
	global_atomic_add v1, v2, s[4:5] offset:1024
.LBB0_271:
	s_or_b64 exec, exec, s[8:9]
	s_waitcnt vmcnt(0)

.LBB0_590:
	s_andn2_saveexec_b64 s[8:9], s[8:9]
	s_cbranch_execz .LBB0_610
	s_mov_b64 s[8:9], exec
	buffer_inv sc1
	buffer_wbl2 sc1
	s_waitcnt lgkmcnt(0)
	s_waitcnt vmcnt(0)
	v_mbcnt_lo_u32_b32 v1, s8, 0
	v_mbcnt_hi_u32_b32 v1, s9, v1
	v_cmp_eq_u32_e32 vcc, 0, v1
	s_and_saveexec_b64 s[10:11], vcc
	s_cbranch_execz .LBB0_593
	s_bcnt1_i32_b64 s5, s[8:9]
	v_readlane_b32 s8, v253, 22
	v_mov_b32_e32 v2, s5
	v_readlane_b32 s9, v253, 23
	s_nop 4
	global_atomic_add v2, v33, v2, s[8:9] sc0

.LBB0_607:
	s_or_b64 exec, exec, s[8:9]
	s_mov_b64 s[8:9], exec
	v_mbcnt_lo_u32_b32 v0, s8, 0
	v_mbcnt_hi_u32_b32 v0, s9, v0
	v_cmp_eq_u32_e32 vcc, 0, v0
	s_and_saveexec_b64 s[10:11], vcc
	s_cbranch_execz .LBB0_609
	s_bcnt1_i32_b64 s5, s[8:9]
	v_readlane_b32 s8, v253, 20
	v_mov_b32_e32 v0, s5
	v_readlane_b32 s9, v253, 21
	s_nop 4
	global_atomic_add v33, v0, s[8:9]
.LBB0_609:
	s_or_b64 exec, exec, s[10:11]
	s_waitcnt vmcnt(0)

.LBB0_865:
	s_or_b64 exec, exec, s[8:9]
	s_mov_b64 s[8:9], exec
	v_mbcnt_lo_u32_b32 v0, s8, 0
	v_mbcnt_hi_u32_b32 v0, s9, v0
	v_cmp_eq_u32_e32 vcc, 0, v0
	s_and_saveexec_b64 s[10:11], vcc
	s_cbranch_execz .LBB0_867
	s_bcnt1_i32_b64 s5, s[8:9]
	v_readlane_b32 s8, v253, 20
	v_mov_b32_e32 v0, s5
	v_readlane_b32 s9, v253, 21
	s_nop 4
	global_atomic_add v33, v0, s[8:9]
.LBB0_867:
	s_or_b64 exec, exec, s[10:11]
	s_waitcnt vmcnt(0)
